# asel: second-part work items of KV blocks 1..8 dealt to blocks by expected total work (balance)
# speedup vs baseline: 1.0033x; 1.0032x over previous
.LBB0_1247:
	s_mul_hi_i32 s0, s71, 0x84210843
	s_add_i32 s0, s0, s71
	s_lshr_b32 s1, s0, 31
	s_ashr_i32 s0, s0, 10
	s_add_i32 s1, s0, s1
	s_mul_i32 s0, s1, 0xfffff840
	s_add_i32 s34, s0, s71
	s_and_b32 s0, s34, 7
	s_mulk_i32 s0, 0xf8
	s_bfe_u32 s4, s34, 0x30003
	s_mulk_i32 s4, 31
	s_add_i32 s0, s0, s4
	s_lshr_b32 s4, s34, 6
	s_cmp_lg_u32 s1, 1
	s_cbranch_scc1 .Lasp_skip
	s_sub_u32 s5, s4, 1
	s_cmp_gt_u32 s5, 7
	s_cbranch_scc1 .Lasp_skip
	s_lshl_b32 s5, s5, 2
	s_lshr_b32 s5, 0x84123576, s5
	s_and_b32 s4, s5, 15
.Lasp_skip:
	s_add_i32 s34, s0, s4
	s_mul_hi_i32 s0, s34, 0x84210843
	s_add_i32 s0, s0, s34
	s_lshr_b32 s4, s0, 31
	s_ashr_i32 s0, s0, 4
	s_add_i32 s0, s0, s4
	s_mul_i32 s14, s0, 0xffffffe1
	s_add_i32 s14, s14, s34
	s_lshl_b32 s4, s14, 8
	s_lshl_b32 s15, s1, 10
	s_sub_i32 s5, 0x1f00, s4
	s_cmp_ge_i32 s15, s5
	s_cbranch_scc1 .LBB0_1246
	s_ashr_i32 s35, s34, 31
	s_lshl_b32 s11, s1, 3
	s_lshl_b64 s[34:35], s[34:35], 2
	s_add_u32 s34, s16, s34
	s_addc_u32 s35, s17, s35
	global_load_dword v110, v101, s[34:35]
	s_waitcnt vmcnt(0)
	v_readfirstlane_b32 s1, v110
	s_addk_i32 s1, 0x7f
	s_ashr_i32 s10, s1, 7
	s_cmp_ge_i32 s11, s10
	s_cbranch_scc1 .LBB0_1246
	s_ashr_i32 s1, s0, 31
	s_lshl_b64 s[38:39], s[0:1], 13
	s_mul_i32 s76, s0, 0x3e000
	s_mul_hi_i32 s77, s0, 0x3e000
	s_add_u32 s76, s28, s76
	s_addc_u32 s77, s29, s77
	s_not_b32 s78, s14
	s_lshl_b32 s78, s78, 7
	s_addk_i32 s78, 0x2000
	s_mul_i32 s78, s78, s14
	s_ashr_i32 s79, s78, 31
	s_lshl_b64 s[78:79], s[78:79], 1
	s_add_u32 s76, s76, s78
	s_addc_u32 s77, s77, s79
	v_add_u32_e32 v178, -1, v110
	v_add_u32_e32 v179, s15, v107
	v_mov_b32_e32 v180, v179
	v_min_i32_e32 v180, v180, v178
	v_lshlrev_b32_e32 v180, 1, v180
	v_add_u32_e32 v181, 0x80, v179
	v_min_i32_e32 v181, v181, v178
	v_lshlrev_b32_e32 v181, 1, v181
	v_add_u32_e32 v182, 0x100, v179
	v_min_i32_e32 v182, v182, v178
	v_lshlrev_b32_e32 v182, 1, v182
	v_add_u32_e32 v183, 0x180, v179
	v_min_i32_e32 v183, v183, v178
	v_lshlrev_b32_e32 v183, 1, v183
	v_add_u32_e32 v184, 0x200, v179
	v_min_i32_e32 v184, v184, v178
	v_lshlrev_b32_e32 v184, 1, v184
	v_add_u32_e32 v185, 0x280, v179
	v_min_i32_e32 v185, v185, v178
	v_lshlrev_b32_e32 v185, 1, v185
	v_add_u32_e32 v186, 0x300, v179
	v_min_i32_e32 v186, v186, v178
	v_lshlrev_b32_e32 v186, 1, v186
	v_add_u32_e32 v187, 0x380, v179
	v_min_i32_e32 v187, v187, v178
	v_lshlrev_b32_e32 v187, 1, v187
	global_load_ushort v170, v180, s[76:77]
	global_load_ushort v171, v181, s[76:77]
	global_load_ushort v172, v182, s[76:77]
	global_load_ushort v173, v183, s[76:77]
	global_load_ushort v174, v184, s[76:77]
	global_load_ushort v175, v185, s[76:77]
	global_load_ushort v176, v186, s[76:77]
	global_load_ushort v177, v187, s[76:77]
	s_ashr_i32 s5, s4, 31
	s_add_u32 s34, s38, s4
	s_addc_u32 s35, s39, s5
	s_lshl_b64 s[34:35], s[34:35], 7
	s_add_u32 s34, s26, s34
	s_addc_u32 s35, s27, s35
	s_lshl_b64 s[36:37], s[0:1], 20
	v_mov_b32_e32 v82, v196
	s_barrier
	s_add_u32 s33, s46, s36
	s_addc_u32 s36, s47, s37
	v_ashrrev_i32_e32 v64, 3, v82
	s_lshl_b64 s[4:5], s[4:5], 1
	v_lshlrev_b32_e32 v32, 4, v82
	v_add_u32_e32 v66, 32, v64
	s_add_u32 s4, s33, s4
	v_and_b32_e32 v100, 0x70, v32
	v_ashrrev_i32_e32 v65, 31, v64
	v_ashrrev_i32_e32 v67, 31, v66
	v_ashrrev_i32_e32 v80, 5, v82
	s_addc_u32 s5, s36, s5
	v_lshl_add_u64 v[24:25], s[34:35], 0, v[100:101]
	v_lshlrev_b64 v[0:1], 7, v[64:65]
	v_lshlrev_b64 v[2:3], 7, v[66:67]
	v_add_u32_e32 v68, 64, v64
	v_add_u32_e32 v70, 0x60, v64
	v_and_b32_e32 v100, 0x1f0, v32
	v_ashrrev_i32_e32 v81, 31, v80
	v_lshl_add_u64 v[0:1], v[24:25], 0, v[0:1]
	v_lshl_add_u64 v[4:5], v[24:25], 0, v[2:3]
	v_ashrrev_i32_e32 v69, 31, v68
	v_ashrrev_i32_e32 v71, 31, v70
	v_lshl_add_u64 v[32:33], s[4:5], 0, v[100:101]
	s_waitcnt lgkmcnt(0)
	v_lshlrev_b64 v[34:35], 14, v[80:81]
	global_load_dwordx4 v[0:3], v[0:1], off
	s_nop 0
	global_load_dwordx4 v[4:7], v[4:5], off
	v_lshlrev_b64 v[8:9], 7, v[68:69]
	v_lshlrev_b64 v[10:11], 7, v[70:71]
	v_add_u32_e32 v72, 0x80, v64
	v_add_u32_e32 v74, 0xa0, v64
	v_lshl_add_u64 v[60:61], v[32:33], 0, v[34:35]
	v_lshl_add_u64 v[8:9], v[24:25], 0, v[8:9]
	v_lshl_add_u64 v[12:13], v[24:25], 0, v[10:11]
	v_ashrrev_i32_e32 v73, 31, v72
	v_ashrrev_i32_e32 v75, 31, v74
	v_add_co_u32_e32 v36, vcc, s62, v60
	global_load_dwordx4 v[8:11], v[8:9], off
	s_nop 0
	global_load_dwordx4 v[12:15], v[12:13], off
	v_lshlrev_b64 v[16:17], 7, v[72:73]
	v_lshlrev_b64 v[18:19], 7, v[74:75]
	v_add_u32_e32 v76, 0xc0, v64
	v_add_u32_e32 v78, 0xe0, v64
	v_addc_co_u32_e32 v37, vcc, 0, v61, vcc
	v_lshl_add_u64 v[16:17], v[24:25], 0, v[16:17]
	v_lshl_add_u64 v[20:21], v[24:25], 0, v[18:19]
	v_ashrrev_i32_e32 v77, 31, v76
	v_ashrrev_i32_e32 v79, 31, v78
	v_add_co_u32_e32 v40, vcc, s63, v60
	global_load_dwordx4 v[16:19], v[16:17], off
	s_nop 0
	global_load_dwordx4 v[20:23], v[20:21], off
	v_lshlrev_b64 v[26:27], 7, v[76:77]
	v_lshlrev_b64 v[28:29], 7, v[78:79]
	v_addc_co_u32_e32 v41, vcc, 0, v61, vcc
	v_lshl_add_u64 v[26:27], v[24:25], 0, v[26:27]
	v_lshl_add_u64 v[28:29], v[24:25], 0, v[28:29]
	v_add_co_u32_e32 v44, vcc, s64, v60
	global_load_dwordx4 v[24:27], v[26:27], off
	s_nop 0
	global_load_dwordx4 v[28:31], v[28:29], off
	v_addc_co_u32_e32 v45, vcc, 0, v61, vcc
	v_add_co_u32_e32 v48, vcc, s65, v60
	global_load_dwordx4 v[32:35], v[60:61], off
	s_nop 0
	global_load_dwordx4 v[36:39], v[36:37], off
	v_addc_co_u32_e32 v49, vcc, 0, v61, vcc
	v_add_co_u32_e32 v52, vcc, s66, v60
	global_load_dwordx4 v[40:43], v[40:41], off
	s_nop 0
	global_load_dwordx4 v[44:47], v[44:45], off
	v_addc_co_u32_e32 v53, vcc, 0, v61, vcc
	v_add_co_u32_e32 v56, vcc, s67, v60
	global_load_dwordx4 v[48:51], v[48:49], off
	s_nop 0
	global_load_dwordx4 v[52:55], v[52:53], off
	v_addc_co_u32_e32 v57, vcc, 0, v61, vcc
	v_add_co_u32_e32 v60, vcc, s68, v60
	global_load_dwordx4 v[56:59], v[56:57], off
	s_nop 0
	v_addc_co_u32_e32 v61, vcc, 0, v61, vcc
	global_load_dwordx4 v[60:63], v[60:61], off
	s_waitcnt vmcnt(16)
	v_and_b32_e32 v178, 0x1fff, v170
	v_or_b32_e32 v178, s38, v178
	v_mov_b32_e32 v179, s39
	v_lshlrev_b64 v[178:179], 7, v[178:179]
	v_lshl_add_u64 v[178:179], v[102:103], 0, v[178:179]
	global_load_dwordx4 v[180:183], v[178:179], off offset:96
	global_load_dwordx4 v[184:187], v[178:179], off offset:64
	global_load_dwordx4 v[188:191], v[178:179], off offset:32
	global_load_dwordx4 v[192:195], v[178:179], off
	v_lshrrev_b32_e32 v65, 1, v64
	v_xor_b32_e32 v65, v65, v82
	v_lshlrev_b32_e32 v65, 4, v65
	v_and_b32_e32 v65, 0x70, v65
	v_add_u32_e32 v65, 16, v65
	v_lshl_add_u32 v64, v64, 7, v65
	s_add_i32 s33, s11, 8
	s_mul_i32 s5, s0, 0x3e000
	s_mul_hi_i32 s4, s0, 0x3e000
	s_add_u32 s34, s28, s5
	s_addc_u32 s35, s29, s4
	s_not_b32 s4, s14
	s_lshl_b32 s4, s4, 7
	s_addk_i32 s4, 0x2000
	s_mul_i32 s4, s4, s14
	s_ashr_i32 s5, s4, 31
	s_lshl_b64 s[4:5], s[4:5], 1
	s_add_u32 s4, s34, s4
	s_addc_u32 s5, s35, s5
	s_or_b32 s34, s11, 1
	s_lshl_b32 s14, s34, 7
	s_waitcnt vmcnt(15)
	ds_write_b128 v64, v[0:3]
	v_lshl_add_u32 v0, v66, 7, v65
	s_waitcnt vmcnt(14)
	ds_write_b128 v0, v[4:7]
	v_lshl_add_u32 v0, v68, 7, v65
	s_min_i32 s10, s33, s10
	s_cmp_ge_i32 s34, s10
	s_cselect_b64 s[40:41], -1, 0
	s_and_b64 vcc, exec, s[40:41]
	s_waitcnt vmcnt(13)
	ds_write_b128 v0, v[8:11]
	v_lshl_add_u32 v0, v70, 7, v65
	s_waitcnt vmcnt(12)
	ds_write_b128 v0, v[12:15]
	v_lshl_add_u32 v0, v72, 7, v65
	v_add_u32_e32 v12, -1, v110
	v_add_u32_e32 v13, s15, v107
	v_add_u32_e32 v2, 0x100, v13
	v_add_u32_e32 v4, 0x180, v13
	v_add_u32_e32 v6, 0x200, v13
	v_add_u32_e32 v8, 0x280, v13
	v_add_u32_e32 v10, 0x300, v13
	v_min_i32_e32 v2, v2, v12
	v_min_i32_e32 v4, v4, v12
	s_waitcnt vmcnt(11)
	ds_write_b128 v0, v[16:19]
	v_lshl_add_u32 v0, v74, 7, v65
	s_waitcnt vmcnt(10)
	ds_write_b128 v0, v[20:23]
	v_lshl_add_u32 v0, v76, 7, v65
	v_min_i32_e32 v6, v6, v12
	v_min_i32_e32 v8, v8, v12
	v_min_i32_e32 v10, v10, v12
	v_ashrrev_i32_e32 v3, 31, v2
	v_ashrrev_i32_e32 v5, 31, v4
	s_waitcnt vmcnt(9)
	ds_write_b128 v0, v[24:27]
	v_lshl_add_u32 v0, v78, 7, v65
	s_waitcnt vmcnt(8)
	ds_write_b128 v0, v[28:31]
	v_mul_lo_u32 v0, v80, s60
	v_add3_u32 v0, 16, v100, v0
	v_add_u32_e32 v1, 0x8000, v0
	s_waitcnt vmcnt(7)
	ds_write2_b64 v1, v[32:33], v[34:35] offset1:1
	v_add_u32_e32 v1, 0x9040, v0
	s_waitcnt vmcnt(6)
	ds_write2_b64 v1, v[36:37], v[38:39] offset1:1
	v_add_u32_e32 v1, 0xa080, v0
	s_waitcnt vmcnt(5)
	ds_write2_b64 v1, v[40:41], v[42:43] offset1:1
	v_add_u32_e32 v1, 0xb0c0, v0
	s_waitcnt vmcnt(4)
	ds_write2_b64 v1, v[44:45], v[46:47] offset1:1
	v_add_u32_e32 v1, 0xc100, v0
	v_ashrrev_i32_e32 v7, 31, v6
	s_waitcnt vmcnt(3)
	ds_write2_b64 v1, v[48:49], v[50:51] offset1:1
	v_add_u32_e32 v1, 0xd140, v0
	s_waitcnt vmcnt(2)
	ds_write2_b64 v1, v[52:53], v[54:55] offset1:1
	v_add_u32_e32 v1, 0xe180, v0
	v_add_u32_e32 v0, 0xf1c0, v0
	v_ashrrev_i32_e32 v9, 31, v8
	s_waitcnt vmcnt(1)
	ds_write2_b64 v1, v[56:57], v[58:59] offset1:1
	v_ashrrev_i32_e32 v11, 31, v10
	v_lshl_add_u64 v[2:3], v[2:3], 1, s[4:5]
	s_waitcnt vmcnt(0)
	ds_write2_b64 v0, v[60:61], v[62:63] offset1:1
	v_min_i32_e32 v0, v13, v12
	v_ashrrev_i32_e32 v1, 31, v0
	v_lshl_add_u64 v[0:1], v[0:1], 1, s[4:5]
	s_waitcnt lgkmcnt(0)
	s_barrier
	v_mov_b32_e32 v100, v170
	v_add_u32_e32 v0, s14, v107
	v_min_i32_e32 v0, v0, v12
	v_add_u32_e32 v13, 0x380, v13
	v_ashrrev_i32_e32 v1, 31, v0
	v_min_i32_e32 v12, v13, v12
	v_lshl_add_u64 v[0:1], v[0:1], 1, s[4:5]
	v_ashrrev_i32_e32 v13, 31, v12
	v_lshl_add_u64 v[4:5], v[4:5], 1, s[4:5]
	v_lshl_add_u64 v[6:7], v[6:7], 1, s[4:5]
	v_lshl_add_u64 v[8:9], v[8:9], 1, s[4:5]
	v_lshl_add_u64 v[10:11], v[10:11], 1, s[4:5]
	v_lshl_add_u64 v[12:13], v[12:13], 1, s[4:5]
	v_mov_b32_e32 v117, v171
	v_mov_b32_e32 v116, v172
	v_mov_b32_e32 v115, v173
	v_mov_b32_e32 v114, v174
	v_mov_b32_e32 v113, v175
	v_mov_b32_e32 v112, v176
	v_mov_b32_e32 v111, v177
	v_mov_b32_e32 v1, s39
	s_waitcnt vmcnt(0)
	v_and_b32_e32 v118, 0x1fff, v100
	v_or_b32_e32 v0, s38, v118
	v_lshlrev_b64 v[0:1], 7, v[0:1]
	v_lshl_add_u64 v[0:1], v[102:103], 0, v[0:1]
	v_mov_b64_e32 v[80:81], v[180:181]
	v_mov_b64_e32 v[82:83], v[182:183]
	v_mov_b64_e32 v[84:85], v[184:185]
	v_mov_b64_e32 v[86:87], v[186:187]
	v_mov_b64_e32 v[88:89], v[188:189]
	v_mov_b64_e32 v[90:91], v[190:191]
	v_mov_b64_e32 v[92:93], v[192:193]
	v_mov_b64_e32 v[94:95], v[194:195]
	s_waitcnt vmcnt(3)
	v_mov_b64_e32 v[64:65], v[80:81]
	s_waitcnt vmcnt(2)
	v_mov_b64_e32 v[68:69], v[84:85]
	s_waitcnt vmcnt(1)
	v_mov_b64_e32 v[72:73], v[88:89]
	s_waitcnt vmcnt(0)
	v_mov_b64_e32 v[76:77], v[92:93]
	v_mov_b64_e32 v[66:67], v[82:83]
	v_mov_b64_e32 v[70:71], v[86:87]
	v_mov_b64_e32 v[74:75], v[90:91]
	v_mov_b64_e32 v[78:79], v[94:95]
	s_cbranch_vccnz .LBB0_1251
	v_and_b32_e32 v0, 0x1fff, v117
	v_or_b32_e32 v0, s38, v0
	v_mov_b32_e32 v1, s39
	v_lshlrev_b64 v[0:1], 7, v[0:1]
	v_lshl_add_u64 v[0:1], v[102:103], 0, v[0:1]
	global_load_dwordx4 v[76:79], v[0:1], off
	global_load_dwordx4 v[72:75], v[0:1], off offset:32
	global_load_dwordx4 v[68:71], v[0:1], off offset:64
	global_load_dwordx4 v[64:67], v[0:1], off offset:96
